# v99 + same residual-epilogue restructure in the FFN2 down instance (lane-exchange index registers moved to v234/v235 to free the xin block)
# baseline (speedup 1.0000x reference)
.LBB0_1560:
	v_lshl_add_u32 v212, s25, 8, v247
	v_lshl_or_b32 v208, s24, 8, v249
	v_ashrrev_i32_e32 v209, 31, v208
	v_ashrrev_i32_e32 v213, 31, v212
	v_lshl_add_u64 v[210:211], v[208:209], 2, s[8:9]
	v_lshlrev_b64 v[130:131], 12, v[212:213]
	v_or_b32_e32 v218, 16, v212
	v_lshl_add_u64 v[130:131], v[210:211], 0, v[130:131]
	v_ashrrev_i32_e32 v219, 31, v218
	global_load_dwordx4 v[194:197], v[130:131], off offset:16
	global_load_dwordx4 v[220:223], v[130:131], off
	global_load_dwordx4 v[178:181], v[130:131], off offset:528
	global_load_dwordx4 v[182:185], v[130:131], off offset:512
	v_lshlrev_b64 v[130:131], 12, v[218:219]
	v_or_b32_e32 v216, 32, v212
	v_lshl_add_u64 v[130:131], v[210:211], 0, v[130:131]
	v_ashrrev_i32_e32 v217, 31, v216
	global_load_dwordx4 v[170:173], v[130:131], off offset:16
	global_load_dwordx4 v[174:177], v[130:131], off
	global_load_dwordx4 v[162:165], v[130:131], off offset:528
	global_load_dwordx4 v[166:169], v[130:131], off offset:512
	v_lshlrev_b64 v[130:131], 12, v[216:217]
	v_or_b32_e32 v214, 48, v212
	v_lshl_add_u64 v[130:131], v[210:211], 0, v[130:131]
	v_ashrrev_i32_e32 v215, 31, v214
	global_load_dwordx4 v[154:157], v[130:131], off offset:16
	global_load_dwordx4 v[158:161], v[130:131], off
	global_load_dwordx4 v[146:149], v[130:131], off offset:528
	global_load_dwordx4 v[150:153], v[130:131], off offset:512
	v_lshlrev_b64 v[130:131], 12, v[214:215]
	v_lshl_add_u64 v[134:135], v[210:211], 0, v[130:131]
	global_load_dwordx4 v[138:141], v[134:135], off offset:16
	global_load_dwordx4 v[142:145], v[134:135], off
	global_load_dwordx4 v[130:133], v[134:135], off offset:528
	s_nop 0
	global_load_dwordx4 v[134:137], v[134:135], off offset:512
	v_lshlrev_b64 v[234:235], 10, v[212:213]
	v_lshl_add_u64 v[234:235], v[234:235], 0, v[208:209]
	s_waitcnt vmcnt(0)
	v_pk_fma_f32 v[122:123], v[122:123], 0.5, v[194:195] op_sel_hi:[1,0,1]
	v_pk_fma_f32 v[128:129], v[128:129], 0.5, v[222:223] op_sel_hi:[1,0,1]
	v_pk_fma_f32 v[126:127], v[126:127], 0.5, v[220:221] op_sel_hi:[1,0,1]
	v_pk_fma_f32 v[124:125], v[124:125], 0.5, v[196:197] op_sel_hi:[1,0,1]
	v_pk_fma_f32 v[120:121], v[120:121], 0.5, v[184:185] op_sel_hi:[1,0,1]
	v_pk_fma_f32 v[118:119], v[118:119], 0.5, v[182:183] op_sel_hi:[1,0,1]
	v_pk_fma_f32 v[116:117], v[116:117], 0.5, v[180:181] op_sel_hi:[1,0,1]
	v_pk_fma_f32 v[114:115], v[114:115], 0.5, v[178:179] op_sel_hi:[1,0,1]
	v_pk_fma_f32 v[110:111], v[110:111], 0.5, v[176:177] op_sel_hi:[1,0,1]
	v_pk_fma_f32 v[108:109], v[108:109], 0.5, v[174:175] op_sel_hi:[1,0,1]
	v_pk_fma_f32 v[106:107], v[106:107], 0.5, v[172:173] op_sel_hi:[1,0,1]
	v_pk_fma_f32 v[104:105], v[104:105], 0.5, v[170:171] op_sel_hi:[1,0,1]
	v_pk_fma_f32 v[102:103], v[102:103], 0.5, v[168:169] op_sel_hi:[1,0,1]
	v_pk_fma_f32 v[100:101], v[100:101], 0.5, v[166:167] op_sel_hi:[1,0,1]
	v_pk_fma_f32 v[98:99], v[98:99], 0.5, v[164:165] op_sel_hi:[1,0,1]
	v_pk_fma_f32 v[96:97], v[96:97], 0.5, v[162:163] op_sel_hi:[1,0,1]
	v_pk_fma_f32 v[94:95], v[94:95], 0.5, v[160:161] op_sel_hi:[1,0,1]
	v_pk_fma_f32 v[92:93], v[92:93], 0.5, v[158:159] op_sel_hi:[1,0,1]
	v_pk_fma_f32 v[90:91], v[90:91], 0.5, v[156:157] op_sel_hi:[1,0,1]
	v_pk_fma_f32 v[88:89], v[88:89], 0.5, v[154:155] op_sel_hi:[1,0,1]
	v_pk_fma_f32 v[86:87], v[86:87], 0.5, v[152:153] op_sel_hi:[1,0,1]
	v_pk_fma_f32 v[84:85], v[84:85], 0.5, v[150:151] op_sel_hi:[1,0,1]
	v_pk_fma_f32 v[82:83], v[82:83], 0.5, v[148:149] op_sel_hi:[1,0,1]
	v_pk_fma_f32 v[80:81], v[80:81], 0.5, v[146:147] op_sel_hi:[1,0,1]
	v_pk_fma_f32 v[78:79], v[78:79], 0.5, v[144:145] op_sel_hi:[1,0,1]
	v_pk_fma_f32 v[76:77], v[76:77], 0.5, v[142:143] op_sel_hi:[1,0,1]
	v_pk_fma_f32 v[74:75], v[74:75], 0.5, v[140:141] op_sel_hi:[1,0,1]
	v_pk_fma_f32 v[72:73], v[72:73], 0.5, v[138:139] op_sel_hi:[1,0,1]
	v_pk_fma_f32 v[70:71], v[70:71], 0.5, v[136:137] op_sel_hi:[1,0,1]
	v_pk_fma_f32 v[68:69], v[68:69], 0.5, v[134:135] op_sel_hi:[1,0,1]
	v_pk_fma_f32 v[66:67], v[66:67], 0.5, v[132:133] op_sel_hi:[1,0,1]
	v_pk_fma_f32 v[64:65], v[64:65], 0.5, v[130:131] op_sel_hi:[1,0,1]
	v_cndmask_b32_e64 v194, 0, 1, s[20:21]
	v_lshl_add_u64 v[222:223], v[234:235], 2, s[10:11]
	v_cmp_ne_u32_e64 s[6:7], 1, v194
	s_andn2_b64 vcc, exec, s[20:21]
	v_lshl_add_u64 v[220:221], v[234:235], 1, s[12:13]
	global_store_dwordx4 v[222:223], v[126:129], off
	global_store_dwordx4 v[222:223], v[122:125], off offset:16
	s_cbranch_vccnz .LBB0_1562
	v_cvt_pk_bf16_f32 v194, v126, v127
	v_cvt_pk_bf16_f32 v195, v128, v129
	v_cvt_pk_bf16_f32 v196, v122, v123
	v_cvt_pk_bf16_f32 v197, v124, v125
	global_store_dwordx4 v[220:221], v[194:197], off
.LBB0_1562:
	s_and_b64 vcc, exec, s[6:7]
	global_store_dwordx4 v[222:223], v[118:121], off offset:512
	global_store_dwordx4 v[222:223], v[114:117], off offset:528
	s_cbranch_vccnz .LBB0_1564
	v_cvt_pk_bf16_f32 v178, v118, v119
	v_cvt_pk_bf16_f32 v179, v120, v121
	v_cvt_pk_bf16_f32 v180, v114, v115
	v_cvt_pk_bf16_f32 v181, v116, v117
	global_store_dwordx4 v[220:221], v[178:181], off offset:256
.LBB0_1564:
	v_add_u32_e32 v182, 0x80, v212
	v_ashrrev_i32_e32 v183, 31, v182
	v_lshlrev_b64 v[182:183], 12, v[182:183]
	v_lshl_add_u64 v[182:183], v[210:211], 0, v[182:183]
	global_load_dwordx4 v[194:197], v[182:183], off offset:16
	global_load_dwordx4 v[220:223], v[182:183], off
	global_load_dwordx4 v[178:181], v[182:183], off offset:528
	s_nop 0
	global_load_dwordx4 v[182:185], v[182:183], off offset:512
	v_add_u32_e32 v166, 0x80, v218
	v_ashrrev_i32_e32 v167, 31, v166
	v_lshlrev_b64 v[166:167], 12, v[166:167]
	v_lshl_add_u64 v[166:167], v[210:211], 0, v[166:167]
	global_load_dwordx4 v[170:173], v[166:167], off offset:16
	global_load_dwordx4 v[174:177], v[166:167], off
	global_load_dwordx4 v[162:165], v[166:167], off offset:528
	s_nop 0
	global_load_dwordx4 v[166:169], v[166:167], off offset:512
	v_add_u32_e32 v150, 0x80, v216
	v_ashrrev_i32_e32 v151, 31, v150
	v_lshlrev_b64 v[150:151], 12, v[150:151]
	v_lshl_add_u64 v[150:151], v[210:211], 0, v[150:151]
	global_load_dwordx4 v[154:157], v[150:151], off offset:16
	global_load_dwordx4 v[158:161], v[150:151], off
	global_load_dwordx4 v[146:149], v[150:151], off offset:528
	s_nop 0
	global_load_dwordx4 v[150:153], v[150:151], off offset:512
	v_add_u32_e32 v134, 0x80, v214
	v_ashrrev_i32_e32 v135, 31, v134
	v_lshlrev_b64 v[134:135], 12, v[134:135]
	v_lshl_add_u64 v[134:135], v[210:211], 0, v[134:135]
	global_load_dwordx4 v[138:141], v[134:135], off offset:16
	global_load_dwordx4 v[142:145], v[134:135], off
	global_load_dwordx4 v[130:133], v[134:135], off offset:528
	s_nop 0
	global_load_dwordx4 v[134:137], v[134:135], off offset:512
	v_mul_f32_e32 v127, v127, v127
	v_fmac_f32_e32 v127, v126, v126
	v_mul_f32_e32 v126, v129, v129
	v_fmac_f32_e32 v126, v128, v128
	v_mul_f32_e32 v123, v123, v123
	v_mul_f32_e32 v119, v119, v119
	v_add_f32_e32 v126, v127, v126
	v_fmac_f32_e32 v123, v122, v122
	v_fmac_f32_e32 v119, v118, v118
	v_mul_f32_e32 v118, v121, v121
	v_add_f32_e32 v122, v123, v126
	v_mul_f32_e32 v123, v125, v125
	v_fmac_f32_e32 v118, v120, v120
	v_mul_f32_e32 v115, v115, v115
	v_fmac_f32_e32 v123, v124, v124
	v_and_b32_e32 v124, 64, v245
	v_add_f32_e32 v118, v119, v118
	v_fmac_f32_e32 v115, v114, v114
	v_add_f32_e32 v122, v123, v122
	v_xor_b32_e32 v123, 16, v245
	v_add_u32_e32 v124, 64, v124
	v_add_f32_e32 v114, v115, v118
	v_mul_f32_e32 v115, v117, v117
	v_cmp_lt_i32_e32 vcc, v123, v124
	v_fmac_f32_e32 v115, v116, v116
	v_add_f32_e32 v114, v115, v114
	v_cndmask_b32_e32 v123, v245, v123, vcc
	v_lshlrev_b32_e32 v234, 2, v123
	v_add_f32_e32 v114, v122, v114
	ds_bpermute_b32 v115, v234, v114
	v_xor_b32_e32 v116, 32, v245
	v_cmp_lt_i32_e32 vcc, v116, v124
	s_lshl_b32 s36, s24, 2
	s_ashr_i32 s37, s36, 31
	v_cndmask_b32_e32 v116, v245, v116, vcc
	v_lshlrev_b32_e32 v235, 2, v116
	s_waitcnt lgkmcnt(0)
	v_add_f32_e32 v114, v114, v115
	ds_bpermute_b32 v115, v235, v114
	s_and_saveexec_b64 s[24:25], s[22:23]
	s_cbranch_execz .LBB0_1566
	v_lshlrev_b64 v[116:117], 6, v[212:213]
	v_lshl_add_u64 v[116:117], s[16:17], 0, v[116:117]
	v_lshl_add_u64 v[116:117], s[36:37], 2, v[116:117]
	s_lshl_b32 s90, s59, 2
	v_lshl_add_u64 v[116:117], v[116:117], 0, s[90:91]
	s_waitcnt lgkmcnt(0)
	v_add_f32_e32 v114, v114, v115
	global_store_dword v[116:117], v114, off
.LBB0_1566:
	s_or_b64 exec, exec, s[24:25]
	s_waitcnt lgkmcnt(0)
	v_lshlrev_b64 v[114:115], 10, v[218:219]
	v_lshl_add_u64 v[114:115], v[114:115], 0, v[208:209]
	v_lshl_add_u64 v[116:117], v[114:115], 2, s[10:11]
	s_and_b64 vcc, exec, s[6:7]
	v_lshl_add_u64 v[114:115], v[114:115], 1, s[12:13]
	global_store_dwordx4 v[116:117], v[108:111], off
	global_store_dwordx4 v[116:117], v[104:107], off offset:16
	s_cbranch_vccnz .LBB0_1568
	v_cvt_pk_bf16_f32 v118, v108, v109
	v_cvt_pk_bf16_f32 v119, v110, v111
	v_cvt_pk_bf16_f32 v120, v104, v105
	v_cvt_pk_bf16_f32 v121, v106, v107
	global_store_dwordx4 v[114:115], v[118:121], off
.LBB0_1568:
	s_and_b64 vcc, exec, s[6:7]
	global_store_dwordx4 v[116:117], v[100:103], off offset:512
	global_store_dwordx4 v[116:117], v[96:99], off offset:528
	s_cbranch_vccnz .LBB0_1570
	v_cvt_pk_bf16_f32 v116, v100, v101
	v_cvt_pk_bf16_f32 v117, v102, v103
	v_cvt_pk_bf16_f32 v118, v96, v97
	v_cvt_pk_bf16_f32 v119, v98, v99
	global_store_dwordx4 v[114:115], v[116:119], off offset:256
.LBB0_1570:
	v_mul_f32_e32 v109, v109, v109
	v_mul_f32_e32 v101, v101, v101
	v_fmac_f32_e32 v109, v108, v108
	v_mul_f32_e32 v108, v111, v111
	v_fmac_f32_e32 v101, v100, v100
	v_mul_f32_e32 v100, v103, v103
	v_fmac_f32_e32 v108, v110, v110
	v_mul_f32_e32 v105, v105, v105
	v_fmac_f32_e32 v100, v102, v102
	v_mul_f32_e32 v97, v97, v97
	v_add_f32_e32 v108, v109, v108
	v_fmac_f32_e32 v105, v104, v104
	v_add_f32_e32 v100, v101, v100
	v_fmac_f32_e32 v97, v96, v96
	v_add_f32_e32 v104, v105, v108
	v_mul_f32_e32 v105, v107, v107
	v_add_f32_e32 v96, v97, v100
	v_mul_f32_e32 v97, v99, v99
	v_fmac_f32_e32 v105, v106, v106
	v_fmac_f32_e32 v97, v98, v98
	v_add_f32_e32 v104, v105, v104
	v_add_f32_e32 v96, v97, v96
	v_add_f32_e32 v96, v104, v96
	ds_bpermute_b32 v97, v234, v96
	s_waitcnt lgkmcnt(0)
	v_add_f32_e32 v96, v96, v97
	ds_bpermute_b32 v97, v235, v96
	s_and_saveexec_b64 s[24:25], s[22:23]
	s_cbranch_execz .LBB0_1572
	v_lshlrev_b64 v[98:99], 6, v[218:219]
	v_lshl_add_u64 v[98:99], s[16:17], 0, v[98:99]
	v_lshl_add_u64 v[98:99], s[36:37], 2, v[98:99]
	s_lshl_b32 s90, s59, 2
	v_lshl_add_u64 v[98:99], v[98:99], 0, s[90:91]
	s_waitcnt lgkmcnt(0)
	v_add_f32_e32 v96, v96, v97
	global_store_dword v[98:99], v96, off
.LBB0_1572:
	s_or_b64 exec, exec, s[24:25]
	s_waitcnt lgkmcnt(0)
	v_lshlrev_b64 v[96:97], 10, v[216:217]
	v_lshl_add_u64 v[96:97], v[96:97], 0, v[208:209]
	v_lshl_add_u64 v[98:99], v[96:97], 2, s[10:11]
	s_and_b64 vcc, exec, s[6:7]
	v_lshl_add_u64 v[96:97], v[96:97], 1, s[12:13]
	global_store_dwordx4 v[98:99], v[92:95], off
	global_store_dwordx4 v[98:99], v[88:91], off offset:16
	s_cbranch_vccnz .LBB0_1574
	v_cvt_pk_bf16_f32 v100, v92, v93
	v_cvt_pk_bf16_f32 v101, v94, v95
	v_cvt_pk_bf16_f32 v102, v88, v89
	v_cvt_pk_bf16_f32 v103, v90, v91
	global_store_dwordx4 v[96:97], v[100:103], off
.LBB0_1574:
	s_and_b64 vcc, exec, s[6:7]
	global_store_dwordx4 v[98:99], v[84:87], off offset:512
	global_store_dwordx4 v[98:99], v[80:83], off offset:528
	s_cbranch_vccnz .LBB0_1576
	v_cvt_pk_bf16_f32 v98, v84, v85
	v_cvt_pk_bf16_f32 v99, v86, v87
	v_cvt_pk_bf16_f32 v100, v80, v81
	v_cvt_pk_bf16_f32 v101, v82, v83
	global_store_dwordx4 v[96:97], v[98:101], off offset:256
.LBB0_1576:
	v_mul_f32_e32 v93, v93, v93
	v_mul_f32_e32 v85, v85, v85
	v_fmac_f32_e32 v93, v92, v92
	v_mul_f32_e32 v92, v95, v95
	v_fmac_f32_e32 v85, v84, v84
	v_mul_f32_e32 v84, v87, v87
	v_fmac_f32_e32 v92, v94, v94
	v_mul_f32_e32 v89, v89, v89
	v_fmac_f32_e32 v84, v86, v86
	v_mul_f32_e32 v81, v81, v81
	v_add_f32_e32 v92, v93, v92
	v_fmac_f32_e32 v89, v88, v88
	v_add_f32_e32 v84, v85, v84
	v_fmac_f32_e32 v81, v80, v80
	v_add_f32_e32 v88, v89, v92
	v_mul_f32_e32 v89, v91, v91
	v_add_f32_e32 v80, v81, v84
	v_mul_f32_e32 v81, v83, v83
	v_fmac_f32_e32 v89, v90, v90
	v_fmac_f32_e32 v81, v82, v82
	v_add_f32_e32 v88, v89, v88
	v_add_f32_e32 v80, v81, v80
	v_add_f32_e32 v80, v88, v80
	ds_bpermute_b32 v81, v234, v80
	s_waitcnt lgkmcnt(0)
	v_add_f32_e32 v80, v80, v81
	ds_bpermute_b32 v81, v235, v80
	s_and_saveexec_b64 s[24:25], s[22:23]
	s_cbranch_execz .LBB0_1578
	v_lshlrev_b64 v[82:83], 6, v[216:217]
	v_lshl_add_u64 v[82:83], s[16:17], 0, v[82:83]
	v_lshl_add_u64 v[82:83], s[36:37], 2, v[82:83]
	s_lshl_b32 s90, s59, 2
	v_lshl_add_u64 v[82:83], v[82:83], 0, s[90:91]
	s_waitcnt lgkmcnt(0)
	v_add_f32_e32 v80, v80, v81
	global_store_dword v[82:83], v80, off
.LBB0_1578:
	s_or_b64 exec, exec, s[24:25]
	s_waitcnt lgkmcnt(0)
	v_lshlrev_b64 v[80:81], 10, v[214:215]
	v_lshl_add_u64 v[80:81], v[80:81], 0, v[208:209]
	v_lshl_add_u64 v[82:83], v[80:81], 2, s[10:11]
	s_and_b64 vcc, exec, s[6:7]
	v_lshl_add_u64 v[80:81], v[80:81], 1, s[12:13]
	global_store_dwordx4 v[82:83], v[76:79], off
	global_store_dwordx4 v[82:83], v[72:75], off offset:16
	s_cbranch_vccnz .LBB0_1580
	v_cvt_pk_bf16_f32 v84, v76, v77
	v_cvt_pk_bf16_f32 v85, v78, v79
	v_cvt_pk_bf16_f32 v86, v72, v73
	v_cvt_pk_bf16_f32 v87, v74, v75
	global_store_dwordx4 v[80:81], v[84:87], off
.LBB0_1580:
	s_and_b64 vcc, exec, s[6:7]
	global_store_dwordx4 v[82:83], v[68:71], off offset:512
	global_store_dwordx4 v[82:83], v[64:67], off offset:528
	s_cbranch_vccnz .LBB0_1582
	v_cvt_pk_bf16_f32 v82, v68, v69
	v_cvt_pk_bf16_f32 v83, v70, v71
	v_cvt_pk_bf16_f32 v84, v64, v65
	v_cvt_pk_bf16_f32 v85, v66, v67
	global_store_dwordx4 v[80:81], v[82:85], off offset:256
.LBB0_1582:
	v_mul_f32_e32 v77, v77, v77
	v_mul_f32_e32 v69, v69, v69
	v_fmac_f32_e32 v77, v76, v76
	v_mul_f32_e32 v76, v79, v79
	v_fmac_f32_e32 v69, v68, v68
	v_mul_f32_e32 v68, v71, v71
	v_fmac_f32_e32 v76, v78, v78
	v_mul_f32_e32 v73, v73, v73
	v_fmac_f32_e32 v68, v70, v70
	v_mul_f32_e32 v65, v65, v65
	v_add_f32_e32 v76, v77, v76
	v_fmac_f32_e32 v73, v72, v72
	v_add_f32_e32 v68, v69, v68
	v_fmac_f32_e32 v65, v64, v64
	v_add_f32_e32 v72, v73, v76
	v_mul_f32_e32 v73, v75, v75
	v_add_f32_e32 v64, v65, v68
	v_mul_f32_e32 v65, v67, v67
	v_fmac_f32_e32 v73, v74, v74
	v_fmac_f32_e32 v65, v66, v66
	v_add_f32_e32 v72, v73, v72
	v_add_f32_e32 v64, v65, v64
	v_add_f32_e32 v64, v72, v64
	ds_bpermute_b32 v65, v234, v64
	s_waitcnt lgkmcnt(0)
	v_add_f32_e32 v64, v64, v65
	ds_bpermute_b32 v65, v235, v64
	s_and_saveexec_b64 s[24:25], s[22:23]
	s_cbranch_execz .LBB0_1584
	v_lshlrev_b64 v[66:67], 6, v[214:215]
	v_lshl_add_u64 v[66:67], s[16:17], 0, v[66:67]
	v_lshl_add_u64 v[66:67], s[36:37], 2, v[66:67]
	s_lshl_b32 s90, s59, 2
	v_lshl_add_u64 v[66:67], v[66:67], 0, s[90:91]
	s_waitcnt lgkmcnt(0)
	v_add_f32_e32 v64, v64, v65
	global_store_dword v[66:67], v64, off
.LBB0_1584:
	s_or_b64 exec, exec, s[24:25]
	s_waitcnt vmcnt(12)
	v_pk_fma_f32 v[62:63], v[62:63], 0.5, v[222:223] op_sel_hi:[1,0,1]
	v_pk_fma_f32 v[60:61], v[60:61], 0.5, v[220:221] op_sel_hi:[1,0,1]
	v_pk_fma_f32 v[58:59], v[58:59], 0.5, v[196:197] op_sel_hi:[1,0,1]
	v_pk_fma_f32 v[56:57], v[56:57], 0.5, v[194:195] op_sel_hi:[1,0,1]
	v_pk_fma_f32 v[54:55], v[54:55], 0.5, v[184:185] op_sel_hi:[1,0,1]
	v_pk_fma_f32 v[52:53], v[52:53], 0.5, v[182:183] op_sel_hi:[1,0,1]
	v_pk_fma_f32 v[50:51], v[50:51], 0.5, v[180:181] op_sel_hi:[1,0,1]
	v_pk_fma_f32 v[48:49], v[48:49], 0.5, v[178:179] op_sel_hi:[1,0,1]
	v_pk_fma_f32 v[46:47], v[46:47], 0.5, v[176:177] op_sel_hi:[1,0,1]
	v_pk_fma_f32 v[44:45], v[44:45], 0.5, v[174:175] op_sel_hi:[1,0,1]
	v_pk_fma_f32 v[42:43], v[42:43], 0.5, v[172:173] op_sel_hi:[1,0,1]
	v_pk_fma_f32 v[40:41], v[40:41], 0.5, v[170:171] op_sel_hi:[1,0,1]
	v_pk_fma_f32 v[38:39], v[38:39], 0.5, v[168:169] op_sel_hi:[1,0,1]
	v_pk_fma_f32 v[36:37], v[36:37], 0.5, v[166:167] op_sel_hi:[1,0,1]
	v_pk_fma_f32 v[34:35], v[34:35], 0.5, v[164:165] op_sel_hi:[1,0,1]
	v_pk_fma_f32 v[32:33], v[32:33], 0.5, v[162:163] op_sel_hi:[1,0,1]
	v_pk_fma_f32 v[30:31], v[30:31], 0.5, v[160:161] op_sel_hi:[1,0,1]
	v_pk_fma_f32 v[28:29], v[28:29], 0.5, v[158:159] op_sel_hi:[1,0,1]
	v_pk_fma_f32 v[26:27], v[26:27], 0.5, v[156:157] op_sel_hi:[1,0,1]
	v_pk_fma_f32 v[24:25], v[24:25], 0.5, v[154:155] op_sel_hi:[1,0,1]
	v_pk_fma_f32 v[22:23], v[22:23], 0.5, v[152:153] op_sel_hi:[1,0,1]
	v_pk_fma_f32 v[20:21], v[20:21], 0.5, v[150:151] op_sel_hi:[1,0,1]
	v_pk_fma_f32 v[18:19], v[18:19], 0.5, v[148:149] op_sel_hi:[1,0,1]
	v_pk_fma_f32 v[16:17], v[16:17], 0.5, v[146:147] op_sel_hi:[1,0,1]
	v_pk_fma_f32 v[14:15], v[14:15], 0.5, v[144:145] op_sel_hi:[1,0,1]
	v_pk_fma_f32 v[12:13], v[12:13], 0.5, v[142:143] op_sel_hi:[1,0,1]
	v_pk_fma_f32 v[10:11], v[10:11], 0.5, v[140:141] op_sel_hi:[1,0,1]
	v_pk_fma_f32 v[8:9], v[8:9], 0.5, v[138:139] op_sel_hi:[1,0,1]
	v_pk_fma_f32 v[6:7], v[6:7], 0.5, v[136:137] op_sel_hi:[1,0,1]
	v_pk_fma_f32 v[4:5], v[4:5], 0.5, v[134:135] op_sel_hi:[1,0,1]
	v_pk_fma_f32 v[2:3], v[2:3], 0.5, v[132:133] op_sel_hi:[1,0,1]
	v_pk_fma_f32 v[0:1], v[0:1], 0.5, v[130:131] op_sel_hi:[1,0,1]
	v_add_u32_e32 v128, 0x80, v212
	v_ashrrev_i32_e32 v129, 31, v128
	s_waitcnt lgkmcnt(0)
	v_add_u32_e32 v126, 0x90, v212
	v_ashrrev_i32_e32 v127, 31, v126
	v_add_u32_e32 v124, 0xa0, v212
	v_ashrrev_i32_e32 v125, 31, v124
	v_add_u32_e32 v122, 0xb0, v212
	v_ashrrev_i32_e32 v123, 31, v122
	v_lshlrev_b64 v[138:139], 10, v[128:129]
	v_lshl_add_u64 v[138:139], v[138:139], 0, v[208:209]
	v_lshl_add_u64 v[132:133], v[138:139], 2, s[10:11]
	s_and_b64 vcc, exec, s[6:7]
	v_lshl_add_u64 v[130:131], v[138:139], 1, s[12:13]
	global_store_dwordx4 v[132:133], v[60:63], off
	global_store_dwordx4 v[132:133], v[56:59], off offset:16
	s_cbranch_vccnz .LBB0_1586
	v_cvt_pk_bf16_f32 v134, v60, v61
	v_cvt_pk_bf16_f32 v135, v62, v63
	v_cvt_pk_bf16_f32 v136, v56, v57
	v_cvt_pk_bf16_f32 v137, v58, v59
	global_store_dwordx4 v[130:131], v[134:137], off
.LBB0_1586:
	s_and_b64 vcc, exec, s[6:7]
	global_store_dwordx4 v[132:133], v[52:55], off offset:512
	global_store_dwordx4 v[132:133], v[48:51], off offset:528
	s_cbranch_vccnz .LBB0_1588
	v_cvt_pk_bf16_f32 v114, v52, v53
	v_cvt_pk_bf16_f32 v115, v54, v55
	v_cvt_pk_bf16_f32 v116, v48, v49
	v_cvt_pk_bf16_f32 v117, v50, v51
	global_store_dwordx4 v[130:131], v[114:117], off offset:256
.LBB0_1588:
	v_mul_f32_e32 v61, v61, v61
	v_mul_f32_e32 v53, v53, v53
	v_fmac_f32_e32 v61, v60, v60
	v_mul_f32_e32 v60, v63, v63
	v_fmac_f32_e32 v53, v52, v52
	v_mul_f32_e32 v52, v55, v55
	v_fmac_f32_e32 v60, v62, v62
	v_mul_f32_e32 v57, v57, v57
	v_fmac_f32_e32 v52, v54, v54
	v_mul_f32_e32 v49, v49, v49
	v_add_f32_e32 v60, v61, v60
	v_fmac_f32_e32 v57, v56, v56
	v_add_f32_e32 v52, v53, v52
	v_fmac_f32_e32 v49, v48, v48
	v_add_f32_e32 v56, v57, v60
	v_mul_f32_e32 v57, v59, v59
	v_add_f32_e32 v48, v49, v52
	v_mul_f32_e32 v49, v51, v51
	v_fmac_f32_e32 v57, v58, v58
	v_fmac_f32_e32 v49, v50, v50
	v_add_f32_e32 v56, v57, v56
	v_add_f32_e32 v48, v49, v48
	v_add_f32_e32 v48, v56, v48
	ds_bpermute_b32 v49, v234, v48
	s_waitcnt lgkmcnt(0)
	v_add_f32_e32 v48, v48, v49
	ds_bpermute_b32 v49, v235, v48
	s_and_saveexec_b64 s[24:25], s[22:23]
	s_cbranch_execz .LBB0_1590
	v_lshlrev_b64 v[50:51], 6, v[128:129]
	v_lshl_add_u64 v[50:51], s[16:17], 0, v[50:51]
	v_lshl_add_u64 v[50:51], s[36:37], 2, v[50:51]
	s_lshl_b32 s90, s59, 2
	v_lshl_add_u64 v[50:51], v[50:51], 0, s[90:91]
	s_waitcnt lgkmcnt(0)
	v_add_f32_e32 v48, v48, v49
	global_store_dword v[50:51], v48, off
.LBB0_1590:
	s_or_b64 exec, exec, s[24:25]
	s_waitcnt lgkmcnt(0)
	v_lshlrev_b64 v[48:49], 10, v[126:127]
	v_lshl_add_u64 v[48:49], v[48:49], 0, v[208:209]
	v_lshl_add_u64 v[50:51], v[48:49], 2, s[10:11]
	s_and_b64 vcc, exec, s[6:7]
	v_lshl_add_u64 v[48:49], v[48:49], 1, s[12:13]
	global_store_dwordx4 v[50:51], v[44:47], off
	global_store_dwordx4 v[50:51], v[40:43], off offset:16
	s_cbranch_vccnz .LBB0_1592
	v_cvt_pk_bf16_f32 v52, v44, v45
	v_cvt_pk_bf16_f32 v53, v46, v47
	v_cvt_pk_bf16_f32 v54, v40, v41
	v_cvt_pk_bf16_f32 v55, v42, v43
	global_store_dwordx4 v[48:49], v[52:55], off
.LBB0_1592:
	s_and_b64 vcc, exec, s[6:7]
	global_store_dwordx4 v[50:51], v[36:39], off offset:512
	global_store_dwordx4 v[50:51], v[32:35], off offset:528
	s_cbranch_vccnz .LBB0_1594
	v_cvt_pk_bf16_f32 v50, v36, v37
	v_cvt_pk_bf16_f32 v51, v38, v39
	v_cvt_pk_bf16_f32 v52, v32, v33
	v_cvt_pk_bf16_f32 v53, v34, v35
	global_store_dwordx4 v[48:49], v[50:53], off offset:256
.LBB0_1594:
	v_mul_f32_e32 v45, v45, v45
	v_mul_f32_e32 v37, v37, v37
	v_fmac_f32_e32 v45, v44, v44
	v_mul_f32_e32 v44, v47, v47
	v_fmac_f32_e32 v37, v36, v36
	v_mul_f32_e32 v36, v39, v39
	v_fmac_f32_e32 v44, v46, v46
	v_mul_f32_e32 v41, v41, v41
	v_fmac_f32_e32 v36, v38, v38
	v_mul_f32_e32 v33, v33, v33
	v_add_f32_e32 v44, v45, v44
	v_fmac_f32_e32 v41, v40, v40
	v_add_f32_e32 v36, v37, v36
	v_fmac_f32_e32 v33, v32, v32
	v_add_f32_e32 v40, v41, v44
	v_mul_f32_e32 v41, v43, v43
	v_add_f32_e32 v32, v33, v36
	v_mul_f32_e32 v33, v35, v35
	v_fmac_f32_e32 v41, v42, v42
	v_fmac_f32_e32 v33, v34, v34
	v_add_f32_e32 v40, v41, v40
	v_add_f32_e32 v32, v33, v32
	v_add_f32_e32 v32, v40, v32
	ds_bpermute_b32 v33, v234, v32
	s_waitcnt lgkmcnt(0)
	v_add_f32_e32 v32, v32, v33
	ds_bpermute_b32 v33, v235, v32
	s_and_saveexec_b64 s[24:25], s[22:23]
	s_cbranch_execz .LBB0_1596
	v_lshlrev_b64 v[34:35], 6, v[126:127]
	v_lshl_add_u64 v[34:35], s[16:17], 0, v[34:35]
	v_lshl_add_u64 v[34:35], s[36:37], 2, v[34:35]
	s_lshl_b32 s90, s59, 2
	v_lshl_add_u64 v[34:35], v[34:35], 0, s[90:91]
	s_waitcnt lgkmcnt(0)
	v_add_f32_e32 v32, v32, v33
	global_store_dword v[34:35], v32, off
.LBB0_1596:
	s_or_b64 exec, exec, s[24:25]
	s_waitcnt lgkmcnt(0)
	v_lshlrev_b64 v[32:33], 10, v[124:125]
	v_lshl_add_u64 v[32:33], v[32:33], 0, v[208:209]
	v_lshl_add_u64 v[34:35], v[32:33], 2, s[10:11]
	s_and_b64 vcc, exec, s[6:7]
	v_lshl_add_u64 v[32:33], v[32:33], 1, s[12:13]
	global_store_dwordx4 v[34:35], v[28:31], off
	global_store_dwordx4 v[34:35], v[24:27], off offset:16
	s_cbranch_vccnz .LBB0_1598
	v_cvt_pk_bf16_f32 v36, v28, v29
	v_cvt_pk_bf16_f32 v37, v30, v31
	v_cvt_pk_bf16_f32 v38, v24, v25
	v_cvt_pk_bf16_f32 v39, v26, v27
	global_store_dwordx4 v[32:33], v[36:39], off
.LBB0_1598:
	s_and_b64 vcc, exec, s[6:7]
	global_store_dwordx4 v[34:35], v[20:23], off offset:512
	global_store_dwordx4 v[34:35], v[16:19], off offset:528
	s_cbranch_vccnz .LBB0_1600
	v_cvt_pk_bf16_f32 v34, v20, v21
	v_cvt_pk_bf16_f32 v35, v22, v23
	v_cvt_pk_bf16_f32 v36, v16, v17
	v_cvt_pk_bf16_f32 v37, v18, v19
	global_store_dwordx4 v[32:33], v[34:37], off offset:256
.LBB0_1600:
	v_mul_f32_e32 v29, v29, v29
	v_mul_f32_e32 v21, v21, v21
	v_fmac_f32_e32 v29, v28, v28
	v_mul_f32_e32 v28, v31, v31
	v_fmac_f32_e32 v21, v20, v20
	v_mul_f32_e32 v20, v23, v23
	v_fmac_f32_e32 v28, v30, v30
	v_mul_f32_e32 v25, v25, v25
	v_fmac_f32_e32 v20, v22, v22
	v_mul_f32_e32 v17, v17, v17
	v_add_f32_e32 v28, v29, v28
	v_fmac_f32_e32 v25, v24, v24
	v_add_f32_e32 v20, v21, v20
	v_fmac_f32_e32 v17, v16, v16
	v_add_f32_e32 v24, v25, v28
	v_mul_f32_e32 v25, v27, v27
	v_add_f32_e32 v16, v17, v20
	v_mul_f32_e32 v17, v19, v19
	v_fmac_f32_e32 v25, v26, v26
	v_fmac_f32_e32 v17, v18, v18
	v_add_f32_e32 v24, v25, v24
	v_add_f32_e32 v16, v17, v16
	v_add_f32_e32 v16, v24, v16
	ds_bpermute_b32 v17, v234, v16
	s_waitcnt lgkmcnt(0)
	v_add_f32_e32 v16, v16, v17
	ds_bpermute_b32 v17, v235, v16
	s_and_saveexec_b64 s[24:25], s[22:23]
	s_cbranch_execz .LBB0_1602
	v_lshlrev_b64 v[18:19], 6, v[124:125]
	v_lshl_add_u64 v[18:19], s[16:17], 0, v[18:19]
	v_lshl_add_u64 v[18:19], s[36:37], 2, v[18:19]
	s_lshl_b32 s90, s59, 2
	v_lshl_add_u64 v[18:19], v[18:19], 0, s[90:91]
	s_waitcnt lgkmcnt(0)
	v_add_f32_e32 v16, v16, v17
	global_store_dword v[18:19], v16, off
.LBB0_1602:
	s_or_b64 exec, exec, s[24:25]
	s_waitcnt lgkmcnt(0)
	v_lshlrev_b64 v[16:17], 10, v[122:123]
	v_lshl_add_u64 v[16:17], v[16:17], 0, v[208:209]
	v_lshl_add_u64 v[18:19], v[16:17], 2, s[10:11]
	s_and_b64 vcc, exec, s[6:7]
	v_lshl_add_u64 v[16:17], v[16:17], 1, s[12:13]
	global_store_dwordx4 v[18:19], v[12:15], off
	global_store_dwordx4 v[18:19], v[8:11], off offset:16
	s_cbranch_vccnz .LBB0_1604
	v_cvt_pk_bf16_f32 v20, v12, v13
	v_cvt_pk_bf16_f32 v21, v14, v15
	v_cvt_pk_bf16_f32 v22, v8, v9
	v_cvt_pk_bf16_f32 v23, v10, v11
	global_store_dwordx4 v[16:17], v[20:23], off
.LBB0_1604:
	s_and_b64 vcc, exec, s[6:7]
	global_store_dwordx4 v[18:19], v[4:7], off offset:512
	global_store_dwordx4 v[18:19], v[0:3], off offset:528
	s_cbranch_vccnz .LBB0_1606
	v_cvt_pk_bf16_f32 v18, v4, v5
	v_cvt_pk_bf16_f32 v19, v6, v7
	v_cvt_pk_bf16_f32 v20, v0, v1
	v_cvt_pk_bf16_f32 v21, v2, v3
	global_store_dwordx4 v[16:17], v[18:21], off offset:256
.LBB0_1606:
	v_mul_f32_e32 v13, v13, v13
	v_mul_f32_e32 v5, v5, v5
	v_fmac_f32_e32 v13, v12, v12
	v_mul_f32_e32 v12, v15, v15
	v_fmac_f32_e32 v5, v4, v4
	v_mul_f32_e32 v4, v7, v7
	v_fmac_f32_e32 v12, v14, v14
	v_mul_f32_e32 v9, v9, v9
	v_fmac_f32_e32 v4, v6, v6
	v_mul_f32_e32 v1, v1, v1
	v_add_f32_e32 v12, v13, v12
	v_fmac_f32_e32 v9, v8, v8
	v_add_f32_e32 v4, v5, v4
	v_fmac_f32_e32 v1, v0, v0
	v_add_f32_e32 v8, v9, v12
	v_mul_f32_e32 v9, v11, v11
	v_add_f32_e32 v0, v1, v4
	v_mul_f32_e32 v1, v3, v3
	v_fmac_f32_e32 v9, v10, v10
	v_fmac_f32_e32 v1, v2, v2
	v_add_f32_e32 v8, v9, v8
	v_add_f32_e32 v0, v1, v0
	v_add_f32_e32 v0, v8, v0
	ds_bpermute_b32 v1, v234, v0
	s_waitcnt lgkmcnt(0)
	v_add_f32_e32 v0, v0, v1
	ds_bpermute_b32 v1, v235, v0
	s_and_saveexec_b64 s[6:7], s[22:23]
	s_cbranch_execz .LBB0_1608
	v_lshlrev_b64 v[2:3], 6, v[122:123]
	v_lshl_add_u64 v[2:3], s[16:17], 0, v[2:3]
	v_lshl_add_u64 v[2:3], s[36:37], 2, v[2:3]
	s_lshl_b32 s90, s59, 2
	v_lshl_add_u64 v[2:3], v[2:3], 0, s[90:91]
	s_waitcnt lgkmcnt(0)
	v_add_f32_e32 v0, v0, v1
	global_store_dword v[2:3], v0, off
